# GEMM loop: removed 6 back-to-back duplicate lgkmcnt(0) waits (on top of 64-bit accumulator zeroing, no tile-start drain)
# speedup vs baseline: 1.0081x; 1.0027x over previous
; #define PG8_STAGE(bufoff, gbase, voff) do { _Pragma("unroll") for (int _i = 0; _i < 2; ++_i) \
;         __builtin_amdgcn_global_load_lds((const unsigned*)((const char*)(gbase) + (voff)[_i]), (LAS unsigned*)(lds + (bufoff) + ldsw + _i * 8192), 16, 0, 0); } while (0)
; #define PG8_LDA(dst, b, h) do { _Pragma("unroll") for (int m = 0; m < 4; ++m) _Pragma("unroll") for (int k = 0; k < 2; ++k) dst[m][k] = *(const LAS h16x8*)(lds + PG8_SA(b, h) + aoff + m * 2048 + k * 1024); } while (0)
; #define PG8_LDB(dst, b, h) do { _Pragma("unroll") for (int n = 0; n < 2; ++n) _Pragma("unroll") for (int k = 0; k < 2; ++k) dst[n][k] = *(const LAS h16x8*)(lds + PG8_SB(b, h) + boff + n * 2048 + k * 1024); } while (0)
; #define PG8_MMA(ai, bj, At, Bt) do { __builtin_amdgcn_s_setprio(1); _Pragma("unroll") for (int m = 0; m < 4; ++m) _Pragma("unroll") for (int n = 0; n < 2; ++n) _Pragma("unroll") for (int k = 0; k < 2; ++k) \
;         acc[ai][bj][m][n] = __builtin_amdgcn_mfma_f32_16x16x32_f16(Bt[n][k], At[m][k], acc[ai][bj][m][n], 0, 0, 0); __builtin_amdgcn_s_setprio(0); } while (0)
; #define PG8_WAIT_V(n) asm volatile("s_waitcnt vmcnt(" #n ")" ::: "memory")
; #define PG8_WAIT_L(n) asm volatile("s_waitcnt lgkmcnt(" #n ")" ::: "memory")
; #define PG8_BAR __builtin_amdgcn_s_barrier()
; #define PG8_SCHED __builtin_amdgcn_sched_barrier(0)
; __device__ __forceinline__ void gemm_phase(LAS unsigned char* lds, const Gemm g, const StaticOrder& S, const Epi& E) {
;     ...
;             PG8_LDB(B0, 0, 0); PG8_SCHED; PG8_LDA(At, 0, 0); PG8_STAGE(PG8_SA(1, 1), a1 + hstepA, voffA);
;             PG8_WAIT_L(8); PG8_BAR; PG8_WAIT_L(0); PG8_MMA(0, 0, At, B0); PG8_BAR; PG8_SCHED;
;             PG8_LDB(B1, 0, 1); PG8_STAGE(PG8_SB(0, 0), b2, voffB);
;             PG8_BAR; PG8_WAIT_L(0); PG8_MMA(0, 1, At, B1); PG8_BAR;
;             PG8_LDA(At, 0, 1); PG8_STAGE(PG8_SA(0, 0), a2, voffA);
;             PG8_BAR; PG8_WAIT_L(0); PG8_MMA(1, 0, At, B0); PG8_BAR; PG8_SCHED;
;             PG8_STAGE(PG8_SB(0, 1), b2 + hstepB, voffB);
;             PG8_WAIT_V(6); PG8_BAR; PG8_MMA(1, 1, At, B1); PG8_BAR;
;             PG8_LDB(B0, 1, 0); PG8_SCHED; PG8_LDA(At, 1, 0); PG8_STAGE(PG8_SA(0, 1), a2 + hstepA, voffA);
;             PG8_WAIT_L(8); PG8_BAR; PG8_WAIT_L(0); PG8_MMA(0, 0, At, B0); PG8_BAR; PG8_SCHED;
.Lprio_skip:
.LBB0_762:
	s_cmp_gt_u32 s34, 15
	s_cselect_b64 s[36:37], -1, 0
	s_and_b64 s[36:37], s[6:7], s[36:37]
	s_and_b64 s[36:37], s[36:37], exec
	s_cselect_b32 s42, 0xfffff000, 0
	s_cselect_b32 s43, -1, 0
	s_add_i32 s38, s34, 2
	s_cmp_gt_u32 s34, 13
	s_cselect_b64 s[36:37], -1, 0
	s_and_b64 s[36:37], s[6:7], s[36:37]
	s_and_b64 s[36:37], s[36:37], exec
	s_cselect_b32 s36, 0xfffff000, 0
	s_cselect_b32 s35, -1, 0
	s_add_u32 s36, s0, s36
	s_addc_u32 s35, s1, s35
	s_add_u32 s36, s36, 0x80
	s_addc_u32 s35, s35, 0
	ds_read_b128 v[128:131], v224
	ds_read_b128 v[132:135], v224 offset:1024
	ds_read_b128 v[136:139], v224 offset:2048
	ds_read_b128 v[140:143], v224 offset:3072
	s_cmp_eq_u32 s66, s34
	s_cselect_b32 s34, s4, s36
	s_cselect_b32 s35, s5, s35
	s_cselect_b32 s37, s29, s33
	s_cselect_b32 s36, s28, s27
	s_add_u32 s86, s0, s42
	s_addc_u32 s87, s1, s43
	s_add_i32 m0, s58, 0xc000
	ds_read_b128 v[144:147], v239
	ds_read_b128 v[148:151], v239 offset:1024
	ds_read_b128 v[152:155], v239 offset:2048
	ds_read_b128 v[156:159], v239 offset:3072
	ds_read_b128 v[160:163], v239 offset:4096
	ds_read_b128 v[164:167], v239 offset:5120
	ds_read_b128 v[168:171], v239 offset:6144
	ds_read_b128 v[172:175], v239 offset:7168
	global_load_lds_dwordx4 v212, s[86:87]
	s_add_i32 m0, s58, 0xe000
	s_nop 0
	global_load_lds_dwordx4 v214, s[86:87]
	s_waitcnt lgkmcnt(8)
	s_barrier
	s_waitcnt lgkmcnt(0)
	v_mfma_f32_16x16x32_f16 v[124:127], v[128:131], v[144:147], v[124:127]
	v_mfma_f32_16x16x32_f16 v[120:123], v[136:139], v[144:147], v[120:123]
	v_mfma_f32_16x16x32_f16 v[108:111], v[128:131], v[152:155], v[108:111]
	v_mfma_f32_16x16x32_f16 v[104:107], v[136:139], v[152:155], v[104:107]
	v_mfma_f32_16x16x32_f16 v[92:95], v[128:131], v[160:163], v[92:95]
	v_mfma_f32_16x16x32_f16 v[88:91], v[136:139], v[160:163], v[88:91]
	v_mfma_f32_16x16x32_f16 v[76:79], v[128:131], v[168:171], v[76:79]
	v_mfma_f32_16x16x32_f16 v[72:75], v[136:139], v[168:171], v[72:75]
	v_mfma_f32_16x16x32_f16 v[124:127], v[132:135], v[148:151], v[124:127]
	v_mfma_f32_16x16x32_f16 v[120:123], v[140:143], v[148:151], v[120:123]
	v_mfma_f32_16x16x32_f16 v[108:111], v[132:135], v[156:159], v[108:111]
	v_mfma_f32_16x16x32_f16 v[104:107], v[140:143], v[156:159], v[104:107]
	v_mfma_f32_16x16x32_f16 v[92:95], v[132:135], v[164:167], v[92:95]
	v_mfma_f32_16x16x32_f16 v[88:91], v[140:143], v[164:167], v[88:91]
	v_mfma_f32_16x16x32_f16 v[76:79], v[132:135], v[172:175], v[76:79]
	v_mfma_f32_16x16x32_f16 v[72:75], v[140:143], v[172:175], v[72:75]
	s_barrier
	s_add_u32 s86, s36, 0x80
	s_addc_u32 s87, s37, 0
	s_add_i32 m0, s31, 0x10000
	ds_read_b128 v[176:179], v225
	ds_read_b128 v[180:183], v225 offset:1024
	ds_read_b128 v[184:187], v225 offset:2048
	ds_read_b128 v[188:191], v225 offset:3072
	global_load_lds_dwordx4 v206, s[36:37]
	s_add_i32 m0, s31, 0x12000
	s_nop 0
	global_load_lds_dwordx4 v210, s[36:37]
	s_barrier
	s_waitcnt lgkmcnt(0)
	v_mfma_f32_16x16x32_f16 v[116:119], v[176:179], v[144:147], v[116:119]
	v_mfma_f32_16x16x32_f16 v[112:115], v[184:187], v[144:147], v[112:115]
	v_mfma_f32_16x16x32_f16 v[100:103], v[176:179], v[152:155], v[100:103]
	v_mfma_f32_16x16x32_f16 v[96:99], v[184:187], v[152:155], v[96:99]
	v_mfma_f32_16x16x32_f16 v[84:87], v[176:179], v[160:163], v[84:87]
	v_mfma_f32_16x16x32_f16 v[80:83], v[184:187], v[160:163], v[80:83]
	v_mfma_f32_16x16x32_f16 v[68:71], v[176:179], v[168:171], v[68:71]
	v_mfma_f32_16x16x32_f16 v[64:67], v[184:187], v[168:171], v[64:67]
	v_mfma_f32_16x16x32_f16 v[116:119], v[180:183], v[148:151], v[116:119]
	v_mfma_f32_16x16x32_f16 v[112:115], v[188:191], v[148:151], v[112:115]
	v_mfma_f32_16x16x32_f16 v[100:103], v[180:183], v[156:159], v[100:103]
	v_mfma_f32_16x16x32_f16 v[96:99], v[188:191], v[156:159], v[96:99]
	v_mfma_f32_16x16x32_f16 v[84:87], v[180:183], v[164:167], v[84:87]
	v_mfma_f32_16x16x32_f16 v[80:83], v[188:191], v[164:167], v[80:83]
	v_mfma_f32_16x16x32_f16 v[68:71], v[180:183], v[172:175], v[68:71]
	v_mfma_f32_16x16x32_f16 v[64:67], v[188:191], v[172:175], v[64:67]
	s_mov_b32 m0, s58
	s_add_u32 s88, s34, 0x80
	s_addc_u32 s89, s35, 0
	s_barrier
	ds_read_b128 v[144:147], v239 offset:16384
	ds_read_b128 v[148:151], v239 offset:17408
	ds_read_b128 v[152:155], v239 offset:18432
	ds_read_b128 v[156:159], v239 offset:19456
	ds_read_b128 v[160:163], v239 offset:20480
	ds_read_b128 v[164:167], v239 offset:21504
	ds_read_b128 v[168:171], v239 offset:22528
	ds_read_b128 v[172:175], v239 offset:23552
	global_load_lds_dwordx4 v204, s[34:35]
	s_mov_b32 m0, s59
	s_nop 0
	global_load_lds_dwordx4 v208, s[34:35]
	s_barrier
	s_waitcnt lgkmcnt(0)
	v_mfma_f32_16x16x32_f16 v[60:63], v[128:131], v[144:147], v[60:63]
	v_mfma_f32_16x16x32_f16 v[56:59], v[136:139], v[144:147], v[56:59]
	v_mfma_f32_16x16x32_f16 v[44:47], v[128:131], v[152:155], v[44:47]
	v_mfma_f32_16x16x32_f16 v[40:43], v[136:139], v[152:155], v[40:43]
	v_mfma_f32_16x16x32_f16 v[28:31], v[128:131], v[160:163], v[28:31]
	v_mfma_f32_16x16x32_f16 v[24:27], v[136:139], v[160:163], v[24:27]
	v_mfma_f32_16x16x32_f16 v[12:15], v[128:131], v[168:171], v[12:15]
	v_mfma_f32_16x16x32_f16 v[8:11], v[136:139], v[168:171], v[8:11]
	v_mfma_f32_16x16x32_f16 v[60:63], v[132:135], v[148:151], v[60:63]
	v_mfma_f32_16x16x32_f16 v[56:59], v[140:143], v[148:151], v[56:59]
	v_mfma_f32_16x16x32_f16 v[44:47], v[132:135], v[156:159], v[44:47]
	v_mfma_f32_16x16x32_f16 v[40:43], v[140:143], v[156:159], v[40:43]
	v_mfma_f32_16x16x32_f16 v[28:31], v[132:135], v[164:167], v[28:31]
	v_mfma_f32_16x16x32_f16 v[24:27], v[140:143], v[164:167], v[24:27]
	v_mfma_f32_16x16x32_f16 v[12:15], v[132:135], v[172:175], v[12:15]
	v_mfma_f32_16x16x32_f16 v[8:11], v[140:143], v[172:175], v[8:11]
	s_barrier
; #define PG8_STAGE(bufoff, gbase, voff) do { _Pragma("unroll") for (int _i = 0; _i < 2; ++_i) \
;         __builtin_amdgcn_global_load_lds((const unsigned*)((const char*)(gbase) + (voff)[_i]), (LAS unsigned*)(lds + (bufoff) + ldsw + _i * 8192), 16, 0, 0); } while (0)
; #define PG8_LDA(dst, b, h) do { _Pragma("unroll") for (int m = 0; m < 4; ++m) _Pragma("unroll") for (int k = 0; k < 2; ++k) dst[m][k] = *(const LAS h16x8*)(lds + PG8_SA(b, h) + aoff + m * 2048 + k * 1024); } while (0)
; #define PG8_LDB(dst, b, h) do { _Pragma("unroll") for (int n = 0; n < 2; ++n) _Pragma("unroll") for (int k = 0; k < 2; ++k) dst[n][k] = *(const LAS h16x8*)(lds + PG8_SB(b, h) + boff + n * 2048 + k * 1024); } while (0)
; #define PG8_MMA(ai, bj, At, Bt) do { __builtin_amdgcn_s_setprio(1); _Pragma("unroll") for (int m = 0; m < 4; ++m) _Pragma("unroll") for (int n = 0; n < 2; ++n) _Pragma("unroll") for (int k = 0; k < 2; ++k) \
;         acc[ai][bj][m][n] = __builtin_amdgcn_mfma_f32_16x16x32_f16(Bt[n][k], At[m][k], acc[ai][bj][m][n], 0, 0, 0); __builtin_amdgcn_s_setprio(0); } while (0)
; #define PG8_WAIT_V(n) asm volatile("s_waitcnt vmcnt(" #n ")" ::: "memory")
; #define PG8_WAIT_L(n) asm volatile("s_waitcnt lgkmcnt(" #n ")" ::: "memory")
; #define PG8_BAR __builtin_amdgcn_s_barrier()
; #define PG8_SCHED __builtin_amdgcn_sched_barrier(0)
; __device__ __forceinline__ void gemm_phase(LAS unsigned char* lds, const Gemm g, const StaticOrder& S, const Epi& E) {
;     ...
;             PG8_WAIT_V(6); PG8_BAR; PG8_MMA(1, 1, At, B1); PG8_BAR;
;             PG8_LDB(B0, 1, 0); PG8_SCHED; PG8_LDA(At, 1, 0); PG8_STAGE(PG8_SA(0, 1), a2 + hstepA, voffA);
;             PG8_WAIT_L(8); PG8_BAR; PG8_WAIT_L(0); PG8_MMA(0, 0, At, B0); PG8_BAR; PG8_SCHED;
;             PG8_LDB(B1, 1, 1); PG8_STAGE(PG8_SB(1, 0), b3, voffB);
;             PG8_BAR; PG8_WAIT_L(0); PG8_MMA(0, 1, At, B1); PG8_BAR;
;             PG8_LDA(At, 1, 1); PG8_STAGE(PG8_SA(1, 0), a3, voffA);
;             PG8_BAR; PG8_WAIT_L(0); PG8_MMA(1, 0, At, B0); PG8_BAR; PG8_SCHED;
	s_add_u32 s36, s36, s18
	s_addc_u32 s37, s37, s19
	s_add_u32 s96, s36, 0x80
	s_addc_u32 s97, s37, 0
	s_add_i32 m0, s31, 0x14000
	s_nop 0
	global_load_lds_dwordx4 v206, s[36:37]
	s_add_i32 m0, s31, 0x16000
	s_nop 0
	global_load_lds_dwordx4 v210, s[36:37]
	s_waitcnt vmcnt(6)
	s_barrier
	v_mfma_f32_16x16x32_f16 v[52:55], v[176:179], v[144:147], v[52:55]
	v_mfma_f32_16x16x32_f16 v[48:51], v[184:187], v[144:147], v[48:51]
	v_mfma_f32_16x16x32_f16 v[36:39], v[176:179], v[152:155], v[36:39]
	v_mfma_f32_16x16x32_f16 v[32:35], v[184:187], v[152:155], v[32:35]
	v_mfma_f32_16x16x32_f16 v[20:23], v[176:179], v[160:163], v[20:23]
	v_mfma_f32_16x16x32_f16 v[16:19], v[184:187], v[160:163], v[16:19]
	v_mfma_f32_16x16x32_f16 v[4:7], v[176:179], v[168:171], v[4:7]
	v_mfma_f32_16x16x32_f16 v[0:3], v[184:187], v[168:171], v[0:3]
	v_mfma_f32_16x16x32_f16 v[52:55], v[180:183], v[148:151], v[52:55]
	v_mfma_f32_16x16x32_f16 v[48:51], v[188:191], v[148:151], v[48:51]
	v_mfma_f32_16x16x32_f16 v[36:39], v[180:183], v[156:159], v[36:39]
	v_mfma_f32_16x16x32_f16 v[32:35], v[188:191], v[156:159], v[32:35]
	v_mfma_f32_16x16x32_f16 v[20:23], v[180:183], v[164:167], v[20:23]
	v_mfma_f32_16x16x32_f16 v[16:19], v[188:191], v[164:167], v[16:19]
	v_mfma_f32_16x16x32_f16 v[4:7], v[180:183], v[172:175], v[4:7]
	v_mfma_f32_16x16x32_f16 v[0:3], v[188:191], v[172:175], v[0:3]
	s_barrier
	ds_read_b128 v[128:131], v241
	ds_read_b128 v[132:135], v241 offset:1024
	ds_read_b128 v[136:139], v241 offset:2048
	ds_read_b128 v[140:143], v241 offset:3072
	s_add_u32 s34, s34, s16
	s_addc_u32 s35, s35, s17
	s_mov_b32 m0, s60
	ds_read_b128 v[144:147], v239 offset:32768
	ds_read_b128 v[148:151], v239 offset:33792
	ds_read_b128 v[152:155], v239 offset:34816
	ds_read_b128 v[156:159], v239 offset:35840
	ds_read_b128 v[160:163], v239 offset:36864
	ds_read_b128 v[164:167], v239 offset:37888
	ds_read_b128 v[168:171], v239 offset:38912
	ds_read_b128 v[172:175], v239 offset:39936
	global_load_lds_dwordx4 v204, s[34:35]
	s_mov_b32 m0, s61
	s_nop 0
	global_load_lds_dwordx4 v208, s[34:35]
	s_waitcnt lgkmcnt(8)
	s_barrier
	s_waitcnt lgkmcnt(0)
	v_mfma_f32_16x16x32_f16 v[124:127], v[128:131], v[144:147], v[124:127]
	v_mfma_f32_16x16x32_f16 v[120:123], v[136:139], v[144:147], v[120:123]
	v_mfma_f32_16x16x32_f16 v[108:111], v[128:131], v[152:155], v[108:111]
	v_mfma_f32_16x16x32_f16 v[104:107], v[136:139], v[152:155], v[104:107]
	v_mfma_f32_16x16x32_f16 v[92:95], v[128:131], v[160:163], v[92:95]
	v_mfma_f32_16x16x32_f16 v[88:91], v[136:139], v[160:163], v[88:91]
	v_mfma_f32_16x16x32_f16 v[76:79], v[128:131], v[168:171], v[76:79]
	v_mfma_f32_16x16x32_f16 v[72:75], v[136:139], v[168:171], v[72:75]
	v_mfma_f32_16x16x32_f16 v[124:127], v[132:135], v[148:151], v[124:127]
	v_mfma_f32_16x16x32_f16 v[120:123], v[140:143], v[148:151], v[120:123]
	v_mfma_f32_16x16x32_f16 v[108:111], v[132:135], v[156:159], v[108:111]
	v_mfma_f32_16x16x32_f16 v[104:107], v[140:143], v[156:159], v[104:107]
	v_mfma_f32_16x16x32_f16 v[92:95], v[132:135], v[164:167], v[92:95]
	v_mfma_f32_16x16x32_f16 v[88:91], v[140:143], v[164:167], v[88:91]
	v_mfma_f32_16x16x32_f16 v[76:79], v[132:135], v[172:175], v[76:79]
	v_mfma_f32_16x16x32_f16 v[72:75], v[140:143], v[172:175], v[72:75]
	s_barrier
	s_add_i32 m0, s31, 0x18000
	ds_read_b128 v[176:179], v248
	ds_read_b128 v[180:183], v248 offset:1024
	ds_read_b128 v[184:187], v248 offset:2048
	ds_read_b128 v[188:191], v248 offset:3072
	global_load_lds_dwordx4 v206, s[86:87]
	s_add_i32 m0, s31, 0x1a000
	s_nop 0
	global_load_lds_dwordx4 v210, s[86:87]
	s_barrier
; #define PG8_STAGE(bufoff, gbase, voff) do { _Pragma("unroll") for (int _i = 0; _i < 2; ++_i) \
;         __builtin_amdgcn_global_load_lds((const unsigned*)((const char*)(gbase) + (voff)[_i]), (LAS unsigned*)(lds + (bufoff) + ldsw + _i * 8192), 16, 0, 0); } while (0)
; #define PG8_LDA(dst, b, h) do { _Pragma("unroll") for (int m = 0; m < 4; ++m) _Pragma("unroll") for (int k = 0; k < 2; ++k) dst[m][k] = *(const LAS h16x8*)(lds + PG8_SA(b, h) + aoff + m * 2048 + k * 1024); } while (0)
; #define PG8_MMA(ai, bj, At, Bt) do { __builtin_amdgcn_s_setprio(1); _Pragma("unroll") for (int m = 0; m < 4; ++m) _Pragma("unroll") for (int n = 0; n < 2; ++n) _Pragma("unroll") for (int k = 0; k < 2; ++k) \
;         acc[ai][bj][m][n] = __builtin_amdgcn_mfma_f32_16x16x32_f16(Bt[n][k], At[m][k], acc[ai][bj][m][n], 0, 0, 0); __builtin_amdgcn_s_setprio(0); } while (0)
; #define PG8_WAIT_V(n) asm volatile("s_waitcnt vmcnt(" #n ")" ::: "memory")
; #define PG8_WAIT_L(n) asm volatile("s_waitcnt lgkmcnt(" #n ")" ::: "memory")
; #define PG8_BAR __builtin_amdgcn_s_barrier()
; #define PG8_SCHED __builtin_amdgcn_sched_barrier(0)
; __device__ __forceinline__ void gemm_phase(LAS unsigned char* lds, const Gemm g, const StaticOrder& S, const Epi& E) {
;     ...
;             PG8_LDA(At, 1, 1); PG8_STAGE(PG8_SA(1, 0), a3, voffA);
;             PG8_BAR; PG8_WAIT_L(0); PG8_MMA(1, 0, At, B0); PG8_BAR; PG8_SCHED;
;             PG8_STAGE(PG8_SB(1, 1), b3 + hstepB, voffB);
;             PG8_WAIT_V(6); PG8_BAR; PG8_MMA(1, 1, At, B1); PG8_BAR;
	s_waitcnt lgkmcnt(0)
	v_mfma_f32_16x16x32_f16 v[116:119], v[176:179], v[144:147], v[116:119]
	v_mfma_f32_16x16x32_f16 v[112:115], v[184:187], v[144:147], v[112:115]
	v_mfma_f32_16x16x32_f16 v[100:103], v[176:179], v[152:155], v[100:103]
	v_mfma_f32_16x16x32_f16 v[96:99], v[184:187], v[152:155], v[96:99]
	v_mfma_f32_16x16x32_f16 v[84:87], v[176:179], v[160:163], v[84:87]
	v_mfma_f32_16x16x32_f16 v[80:83], v[184:187], v[160:163], v[80:83]
	v_mfma_f32_16x16x32_f16 v[68:71], v[176:179], v[168:171], v[68:71]
	v_mfma_f32_16x16x32_f16 v[64:67], v[184:187], v[168:171], v[64:67]
	v_mfma_f32_16x16x32_f16 v[116:119], v[180:183], v[148:151], v[116:119]
	v_mfma_f32_16x16x32_f16 v[112:115], v[188:191], v[148:151], v[112:115]
	v_mfma_f32_16x16x32_f16 v[100:103], v[180:183], v[156:159], v[100:103]
	v_mfma_f32_16x16x32_f16 v[96:99], v[188:191], v[156:159], v[96:99]
	v_mfma_f32_16x16x32_f16 v[84:87], v[180:183], v[164:167], v[84:87]
	v_mfma_f32_16x16x32_f16 v[80:83], v[188:191], v[164:167], v[80:83]
	v_mfma_f32_16x16x32_f16 v[68:71], v[180:183], v[172:175], v[68:71]
	v_mfma_f32_16x16x32_f16 v[64:67], v[188:191], v[172:175], v[64:67]
	s_mov_b32 m0, s62
	s_barrier
	ds_read_b128 v[144:147], v239 offset:49152
	ds_read_b128 v[148:151], v239 offset:50176
	ds_read_b128 v[152:155], v239 offset:51200
	ds_read_b128 v[156:159], v239 offset:52224
	ds_read_b128 v[160:163], v239 offset:53248
	ds_read_b128 v[164:167], v239 offset:54272
	ds_read_b128 v[168:171], v239 offset:55296
	ds_read_b128 v[172:175], v239 offset:56320
	global_load_lds_dwordx4 v204, s[88:89]
	s_mov_b32 m0, s63
	s_nop 0
	global_load_lds_dwordx4 v208, s[88:89]
	s_barrier
	s_waitcnt lgkmcnt(0)
	v_mfma_f32_16x16x32_f16 v[60:63], v[128:131], v[144:147], v[60:63]
	v_mfma_f32_16x16x32_f16 v[56:59], v[136:139], v[144:147], v[56:59]
	v_mfma_f32_16x16x32_f16 v[44:47], v[128:131], v[152:155], v[44:47]
	v_mfma_f32_16x16x32_f16 v[40:43], v[136:139], v[152:155], v[40:43]
	v_mfma_f32_16x16x32_f16 v[28:31], v[128:131], v[160:163], v[28:31]
	v_mfma_f32_16x16x32_f16 v[24:27], v[136:139], v[160:163], v[24:27]
	v_mfma_f32_16x16x32_f16 v[12:15], v[128:131], v[168:171], v[12:15]
	v_mfma_f32_16x16x32_f16 v[8:11], v[136:139], v[168:171], v[8:11]
	v_mfma_f32_16x16x32_f16 v[60:63], v[132:135], v[148:151], v[60:63]
	v_mfma_f32_16x16x32_f16 v[56:59], v[140:143], v[148:151], v[56:59]
	v_mfma_f32_16x16x32_f16 v[44:47], v[132:135], v[156:159], v[44:47]
	v_mfma_f32_16x16x32_f16 v[40:43], v[140:143], v[156:159], v[40:43]
	v_mfma_f32_16x16x32_f16 v[28:31], v[132:135], v[164:167], v[28:31]
	v_mfma_f32_16x16x32_f16 v[24:27], v[140:143], v[164:167], v[24:27]
	v_mfma_f32_16x16x32_f16 v[12:15], v[132:135], v[172:175], v[12:15]
	v_mfma_f32_16x16x32_f16 v[8:11], v[140:143], v[172:175], v[8:11]
	s_barrier
	s_add_i32 m0, s31, 0x1c000
	s_nop 0
	global_load_lds_dwordx4 v206, s[96:97]
	s_add_i32 m0, s31, 0x1e000
	s_nop 0
	global_load_lds_dwordx4 v210, s[96:97]
	s_waitcnt vmcnt(6)
	s_barrier
	v_mfma_f32_16x16x32_f16 v[52:55], v[176:179], v[144:147], v[52:55]
	v_mfma_f32_16x16x32_f16 v[48:51], v[184:187], v[144:147], v[48:51]
	v_mfma_f32_16x16x32_f16 v[36:39], v[176:179], v[152:155], v[36:39]
	v_mfma_f32_16x16x32_f16 v[32:35], v[184:187], v[152:155], v[32:35]
	v_mfma_f32_16x16x32_f16 v[20:23], v[176:179], v[160:163], v[20:23]
	v_mfma_f32_16x16x32_f16 v[16:19], v[184:187], v[160:163], v[16:19]
	v_mfma_f32_16x16x32_f16 v[4:7], v[176:179], v[168:171], v[4:7]
	v_mfma_f32_16x16x32_f16 v[0:3], v[184:187], v[168:171], v[0:3]
	v_mfma_f32_16x16x32_f16 v[52:55], v[180:183], v[148:151], v[52:55]
	v_mfma_f32_16x16x32_f16 v[48:51], v[188:191], v[148:151], v[48:51]
	v_mfma_f32_16x16x32_f16 v[36:39], v[180:183], v[156:159], v[36:39]
	v_mfma_f32_16x16x32_f16 v[32:35], v[188:191], v[156:159], v[32:35]
	v_mfma_f32_16x16x32_f16 v[20:23], v[180:183], v[164:167], v[20:23]
	v_mfma_f32_16x16x32_f16 v[16:19], v[188:191], v[164:167], v[16:19]
	v_mfma_f32_16x16x32_f16 v[4:7], v[180:183], v[172:175], v[4:7]
	v_mfma_f32_16x16x32_f16 v[0:3], v[188:191], v[172:175], v[0:3]
	s_add_u32 s0, s0, 0x100
	s_addc_u32 s1, s1, 0
	s_add_u32 s27, s27, 0x100
	s_addc_u32 s33, s33, 0
	s_cmp_ge_u32 s38, s64
	s_mov_b32 s34, s38
	s_barrier
	s_cbranch_scc0 .LBB0_762
	s_setprio 0
	s_lshl_b32 s0, s84, 8
	s_or_b32 s27, s0, s65
	v_lshl_add_u32 v240, s30, 8, v200
	v_or_b32_e32 v216, s27, v202
	s_cmp_eq_u32 s93, 3
	s_cbranch_scc1 .Lst16_fast
	s_cmp_eq_u32 s93, 1
	s_cbranch_scc0 .Llora_no
	s_lshr_b32 s0, s84, 2
	s_cmp_lt_u32 s0, 2
	s_cbranch_scc1 .Llora_fast
